# P9 and P7 main epilogues: bf16 residual loads widened (dwordx4 at swizzled lane address + permlane16_swap back), 16 instead of 32 loads per wave
# baseline (speedup 1.0000x reference)
; __device__ __forceinline__ unsigned cvt_pk_bf16(float lo, float hi) { unsigned r; asm volatile("v_cvt_pk_bf16_f32 %0, %1, %2" : "=v"(r) : "v"(lo), "v"(hi)); return r; }
;     __device__ __forceinline__ void operator()(const f32x4 (&acc)[2][2][4][2], const pg8::Unit& u, int wr, int wc, int fr, int fq) const {
;         const int row0 = u.pm * 256 + wr * 64 + fr, col0 = u.pn * 256 + wc * 32 + 4 * fq;
; #pragma unroll
;         for (int ai = 0; ai < 2; ++ai)
; #pragma unroll
;             for (int m = 0; m < 4; ++m) { const int row = row0 + ai * 128 + m * 16;
;                 if (row < MV) {
;                     const float* rp = (row < MPR) ? res_p + (size_t)row * DM : res_s + (size_t)(row - MPR) * DM;
;                     float s = 0.f;
; #pragma unroll
;                     for (int bj = 0; bj < 2; ++bj)
; #pragma unroll
;                         for (int n = 0; n < 2; ++n) { const int col = col0 + bj * 128 + n * 16; f32x4 r;
;                             if (RESB) { const u32x2 rw = *(const u32x2*)(resb + (size_t)row * DM + col); r = (f32x4){bf2f(rw.x & 0xffff), bf2f(rw.x >> 16), bf2f(rw.y & 0xffff), bf2f(rw.y >> 16)}; }
;                             else r = *(const f32x4*)(rp + col);
;                             const f32x4 v = r + acc[ai][bj][m][n] * scale;
;                             if (OUTF) *(f32x4*)(out + (size_t)row * DM + col) = v;
;                             else { u32x2 w; w.x = cvt_pk_bf16(v[0], v[1]); w.y = cvt_pk_bf16(v[2], v[3]); *(u32x2*)(outb + (size_t)row * DM + col) = w;
;                                 s += (v[0] * v[0] + v[1] * v[1]) + (v[2] * v[2] + v[3] * v[3]); } }
;                     if (!OUTF) { s += __shfl_xor(s, 16); s += __shfl_xor(s, 32); if (fq == 0) atomicAdd(ss + row, s); }
.LBB0_1056:
	s_cmp_lt_i32 s76, 2
	s_cbranch_scc0 .LBB0_1086
	v_lshl_add_u32 v160, s46, 8, v164
	v_lshl_or_b32 v161, s44, 8, v166
	v_lshlrev_b32_e32 v160, 11, v160
	v_lshl_add_u32 v160, v161, 1, v160
	v_bfe_u32 v174, v170, 4, 1
	v_mul_u32_u24_e32 v174, 24, v174
	v_add_u32_e32 v174, v174, v160
	global_load_dwordx4 v[176:179], v174, s[16:17]
	global_load_dwordx4 v[180:183], v174, s[16:17] offset:256
	v_add_u32_e32 v161, 0x8000, v174
	global_load_dwordx4 v[184:187], v161, s[16:17]
	global_load_dwordx4 v[188:191], v161, s[16:17] offset:256
	v_add_u32_e32 v161, 0x10000, v174
	global_load_dwordx4 v[192:195], v161, s[16:17]
	global_load_dwordx4 v[196:199], v161, s[16:17] offset:256
	v_add_u32_e32 v161, 0x18000, v174
	global_load_dwordx4 v[200:203], v161, s[16:17]
	global_load_dwordx4 v[204:207], v161, s[16:17] offset:256
	v_add_u32_e32 v161, 0x40000, v174
	global_load_dwordx4 v[208:211], v161, s[16:17]
	global_load_dwordx4 v[212:215], v161, s[16:17] offset:256
	v_add_u32_e32 v161, 0x48000, v174
	global_load_dwordx4 v[144:147], v161, s[16:17]
	global_load_dwordx4 v[148:151], v161, s[16:17] offset:256
	v_add_u32_e32 v161, 0x50000, v174
	global_load_dwordx4 v[152:155], v161, s[16:17]
	global_load_dwordx4 v[156:159], v161, s[16:17] offset:256
	s_waitcnt vmcnt(12)
	v_permlane16_swap_b32_e32 v176, v178
	v_permlane16_swap_b32_e32 v177, v179
	v_permlane16_swap_b32_e32 v180, v182
	v_permlane16_swap_b32_e32 v181, v183
	v_and_b32_e32 v162, 0xffff0000, v176
	v_lshlrev_b32_e32 v176, 16, v176
	v_and_b32_e32 v163, 0xffff0000, v177
	v_lshlrev_b32_e32 v177, 16, v177
	v_add_f32_e32 v64, v64, v176
	v_add_f32_e32 v65, v65, v162
	v_add_f32_e32 v66, v66, v177
	v_add_f32_e32 v67, v67, v163
	v_mul_f32_e32 v176, v65, v65
	v_mul_f32_e32 v177, v67, v67
	v_fmac_f32_e32 v176, v64, v64
	v_fmac_f32_e32 v177, v66, v66
	v_add_f32_e32 v176, v176, v177
	v_mov_b32_e32 v172, v176
	v_cvt_pk_bf16_f32 v64, v64, v65
	v_cvt_pk_bf16_f32 v65, v66, v67
	v_and_b32_e32 v162, 0xffff0000, v178
	v_lshlrev_b32_e32 v178, 16, v178
	v_and_b32_e32 v163, 0xffff0000, v179
	v_lshlrev_b32_e32 v179, 16, v179
	v_add_f32_e32 v60, v60, v178
	v_add_f32_e32 v61, v61, v162
	v_add_f32_e32 v62, v62, v179
	v_add_f32_e32 v63, v63, v163
	v_mul_f32_e32 v178, v61, v61
	v_mul_f32_e32 v179, v63, v63
	v_fmac_f32_e32 v178, v60, v60
	v_fmac_f32_e32 v179, v62, v62
	v_add_f32_e32 v178, v178, v179
	v_add_f32_e32 v172, v172, v178
	v_cvt_pk_bf16_f32 v66, v60, v61
	v_cvt_pk_bf16_f32 v67, v62, v63
	v_and_b32_e32 v162, 0xffff0000, v180
	v_lshlrev_b32_e32 v180, 16, v180
	v_and_b32_e32 v163, 0xffff0000, v181
	v_lshlrev_b32_e32 v181, 16, v181
	v_add_f32_e32 v52, v52, v180
	v_add_f32_e32 v53, v53, v162
	v_add_f32_e32 v54, v54, v181
	v_add_f32_e32 v55, v55, v163
	v_mul_f32_e32 v180, v53, v53
	v_mul_f32_e32 v181, v55, v55
	v_fmac_f32_e32 v180, v52, v52
	v_fmac_f32_e32 v181, v54, v54
	v_add_f32_e32 v180, v180, v181
	v_add_f32_e32 v172, v172, v180
	v_cvt_pk_bf16_f32 v52, v52, v53
	v_cvt_pk_bf16_f32 v53, v54, v55
	v_and_b32_e32 v162, 0xffff0000, v182
	v_lshlrev_b32_e32 v182, 16, v182
	v_and_b32_e32 v163, 0xffff0000, v183
	v_lshlrev_b32_e32 v183, 16, v183
	v_add_f32_e32 v44, v44, v182
	v_add_f32_e32 v45, v45, v162
	v_add_f32_e32 v46, v46, v183
	v_add_f32_e32 v47, v47, v163
	v_mul_f32_e32 v182, v45, v45
	v_mul_f32_e32 v183, v47, v47
	v_fmac_f32_e32 v182, v44, v44
	v_fmac_f32_e32 v183, v46, v46
	v_add_f32_e32 v182, v182, v183
	v_add_f32_e32 v172, v172, v182
	v_cvt_pk_bf16_f32 v54, v44, v45
	v_cvt_pk_bf16_f32 v55, v46, v47
	v_mov_b32_e32 v60, v172
	v_add_u32_e32 v161, 0x58000, v174
	global_load_dwordx4 v[176:179], v161, s[16:17]
	global_load_dwordx4 v[180:183], v161, s[16:17] offset:256
	s_nop 1
	v_permlane16_swap_b32_e32 v64, v66
	v_permlane16_swap_b32_e32 v65, v67
	v_permlane16_swap_b32_e32 v52, v54
	v_permlane16_swap_b32_e32 v53, v55
	global_store_dwordx4 v174, v[64:67], s[18:19]
	global_store_dwordx4 v174, v[52:55], s[18:19] offset:256
	s_waitcnt vmcnt(14)
	v_permlane16_swap_b32_e32 v184, v186
	v_permlane16_swap_b32_e32 v185, v187
	v_permlane16_swap_b32_e32 v188, v190
	v_permlane16_swap_b32_e32 v189, v191
	v_and_b32_e32 v162, 0xffff0000, v184
	v_lshlrev_b32_e32 v184, 16, v184
	v_and_b32_e32 v163, 0xffff0000, v185
	v_lshlrev_b32_e32 v185, 16, v185
	v_add_f32_e32 v48, v48, v184
	v_add_f32_e32 v49, v49, v162
	v_add_f32_e32 v50, v50, v185
	v_add_f32_e32 v51, v51, v163
	v_mul_f32_e32 v184, v49, v49
	v_mul_f32_e32 v185, v51, v51
	v_fmac_f32_e32 v184, v48, v48
	v_fmac_f32_e32 v185, v50, v50
	v_add_f32_e32 v184, v184, v185
	v_mov_b32_e32 v172, v184
	v_cvt_pk_bf16_f32 v48, v48, v49
	v_cvt_pk_bf16_f32 v49, v50, v51
	v_and_b32_e32 v162, 0xffff0000, v186
	v_lshlrev_b32_e32 v186, 16, v186
	v_and_b32_e32 v163, 0xffff0000, v187
	v_lshlrev_b32_e32 v187, 16, v187
	v_add_f32_e32 v40, v40, v186
	v_add_f32_e32 v41, v41, v162
	v_add_f32_e32 v42, v42, v187
	v_add_f32_e32 v43, v43, v163
	v_mul_f32_e32 v186, v41, v41
	v_mul_f32_e32 v187, v43, v43
	v_fmac_f32_e32 v186, v40, v40
	v_fmac_f32_e32 v187, v42, v42
	v_add_f32_e32 v186, v186, v187
	v_add_f32_e32 v172, v172, v186
	v_cvt_pk_bf16_f32 v50, v40, v41
	v_cvt_pk_bf16_f32 v51, v42, v43
	v_and_b32_e32 v162, 0xffff0000, v188
	v_lshlrev_b32_e32 v188, 16, v188
	v_and_b32_e32 v163, 0xffff0000, v189
	v_lshlrev_b32_e32 v189, 16, v189
	v_add_f32_e32 v36, v36, v188
	v_add_f32_e32 v37, v37, v162
	v_add_f32_e32 v38, v38, v189
	v_add_f32_e32 v39, v39, v163
	v_mul_f32_e32 v188, v37, v37
	v_mul_f32_e32 v189, v39, v39
	v_fmac_f32_e32 v188, v36, v36
	v_fmac_f32_e32 v189, v38, v38
	v_add_f32_e32 v188, v188, v189
	v_add_f32_e32 v172, v172, v188
	v_cvt_pk_bf16_f32 v36, v36, v37
	v_cvt_pk_bf16_f32 v37, v38, v39
	v_and_b32_e32 v162, 0xffff0000, v190
	v_lshlrev_b32_e32 v190, 16, v190
	v_and_b32_e32 v163, 0xffff0000, v191
	v_lshlrev_b32_e32 v191, 16, v191
	v_add_f32_e32 v28, v28, v190
	v_add_f32_e32 v29, v29, v162
	v_add_f32_e32 v30, v30, v191
	v_add_f32_e32 v31, v31, v163
	v_mul_f32_e32 v190, v29, v29
	v_mul_f32_e32 v191, v31, v31
	v_fmac_f32_e32 v190, v28, v28
	v_fmac_f32_e32 v191, v30, v30
	v_add_f32_e32 v190, v190, v191
	v_add_f32_e32 v172, v172, v190
	v_cvt_pk_bf16_f32 v38, v28, v29
	v_cvt_pk_bf16_f32 v39, v30, v31
	v_mov_b32_e32 v40, v172
	v_add_u32_e32 v161, 0x8000, v174
	s_nop 1
	v_permlane16_swap_b32_e32 v48, v50
	v_permlane16_swap_b32_e32 v49, v51
	v_permlane16_swap_b32_e32 v36, v38
	v_permlane16_swap_b32_e32 v37, v39
	global_store_dwordx4 v161, v[48:51], s[18:19]
	global_store_dwordx4 v161, v[36:39], s[18:19] offset:256
	s_waitcnt vmcnt(14)
; __device__ __forceinline__ unsigned cvt_pk_bf16(float lo, float hi) { unsigned r; asm volatile("v_cvt_pk_bf16_f32 %0, %1, %2" : "=v"(r) : "v"(lo), "v"(hi)); return r; }
;     __device__ __forceinline__ void operator()(const f32x4 (&acc)[2][2][4][2], const pg8::Unit& u, int wr, int wc, int fr, int fq) const {
;     ...
;                     for (int bj = 0; bj < 2; ++bj)
; #pragma unroll
;                         for (int n = 0; n < 2; ++n) { const int col = col0 + bj * 128 + n * 16; f32x4 r;
;                             if (RESB) { const u32x2 rw = *(const u32x2*)(resb + (size_t)row * DM + col); r = (f32x4){bf2f(rw.x & 0xffff), bf2f(rw.x >> 16), bf2f(rw.y & 0xffff), bf2f(rw.y >> 16)}; }
;                             else r = *(const f32x4*)(rp + col);
;                             const f32x4 v = r + acc[ai][bj][m][n] * scale;
;                             if (OUTF) *(f32x4*)(out + (size_t)row * DM + col) = v;
;                             else { u32x2 w; w.x = cvt_pk_bf16(v[0], v[1]); w.y = cvt_pk_bf16(v[2], v[3]); *(u32x2*)(outb + (size_t)row * DM + col) = w;
;                                 s += (v[0] * v[0] + v[1] * v[1]) + (v[2] * v[2] + v[3] * v[3]); } }
	v_permlane16_swap_b32_e32 v192, v194
	v_permlane16_swap_b32_e32 v193, v195
	v_permlane16_swap_b32_e32 v196, v198
	v_permlane16_swap_b32_e32 v197, v199
	v_and_b32_e32 v162, 0xffff0000, v192
	v_lshlrev_b32_e32 v192, 16, v192
	v_and_b32_e32 v163, 0xffff0000, v193
	v_lshlrev_b32_e32 v193, 16, v193
	v_add_f32_e32 v32, v32, v192
	v_add_f32_e32 v33, v33, v162
	v_add_f32_e32 v34, v34, v193
	v_add_f32_e32 v35, v35, v163
	v_mul_f32_e32 v192, v33, v33
	v_mul_f32_e32 v193, v35, v35
	v_fmac_f32_e32 v192, v32, v32
	v_fmac_f32_e32 v193, v34, v34
	v_add_f32_e32 v192, v192, v193
	v_mov_b32_e32 v172, v192
	v_cvt_pk_bf16_f32 v32, v32, v33
	v_cvt_pk_bf16_f32 v33, v34, v35
	v_and_b32_e32 v162, 0xffff0000, v194
	v_lshlrev_b32_e32 v194, 16, v194
	v_and_b32_e32 v163, 0xffff0000, v195
	v_lshlrev_b32_e32 v195, 16, v195
	v_add_f32_e32 v24, v24, v194
	v_add_f32_e32 v25, v25, v162
	v_add_f32_e32 v26, v26, v195
	v_add_f32_e32 v27, v27, v163
	v_mul_f32_e32 v194, v25, v25
	v_mul_f32_e32 v195, v27, v27
	v_fmac_f32_e32 v194, v24, v24
	v_fmac_f32_e32 v195, v26, v26
	v_add_f32_e32 v194, v194, v195
	v_add_f32_e32 v172, v172, v194
	v_cvt_pk_bf16_f32 v34, v24, v25
	v_cvt_pk_bf16_f32 v35, v26, v27
	v_and_b32_e32 v162, 0xffff0000, v196
	v_lshlrev_b32_e32 v196, 16, v196
	v_and_b32_e32 v163, 0xffff0000, v197
	v_lshlrev_b32_e32 v197, 16, v197
	v_add_f32_e32 v20, v20, v196
	v_add_f32_e32 v21, v21, v162
	v_add_f32_e32 v22, v22, v197
	v_add_f32_e32 v23, v23, v163
	v_mul_f32_e32 v196, v21, v21
	v_mul_f32_e32 v197, v23, v23
	v_fmac_f32_e32 v196, v20, v20
	v_fmac_f32_e32 v197, v22, v22
	v_add_f32_e32 v196, v196, v197
	v_add_f32_e32 v172, v172, v196
	v_cvt_pk_bf16_f32 v20, v20, v21
	v_cvt_pk_bf16_f32 v21, v22, v23
	v_and_b32_e32 v162, 0xffff0000, v198
	v_lshlrev_b32_e32 v198, 16, v198
	v_and_b32_e32 v163, 0xffff0000, v199
	v_lshlrev_b32_e32 v199, 16, v199
	v_add_f32_e32 v12, v12, v198
	v_add_f32_e32 v13, v13, v162
	v_add_f32_e32 v14, v14, v199
	v_add_f32_e32 v15, v15, v163
	v_mul_f32_e32 v198, v13, v13
	v_mul_f32_e32 v199, v15, v15
	v_fmac_f32_e32 v198, v12, v12
	v_fmac_f32_e32 v199, v14, v14
	v_add_f32_e32 v198, v198, v199
	v_add_f32_e32 v172, v172, v198
	v_cvt_pk_bf16_f32 v22, v12, v13
	v_cvt_pk_bf16_f32 v23, v14, v15
	v_mov_b32_e32 v24, v172
	v_add_u32_e32 v161, 0x10000, v174
	s_nop 1
	v_permlane16_swap_b32_e32 v32, v34
	v_permlane16_swap_b32_e32 v33, v35
	v_permlane16_swap_b32_e32 v20, v22
	v_permlane16_swap_b32_e32 v21, v23
	global_store_dwordx4 v161, v[32:35], s[18:19]
	global_store_dwordx4 v161, v[20:23], s[18:19] offset:256
	s_waitcnt vmcnt(14)
	v_permlane16_swap_b32_e32 v200, v202
	v_permlane16_swap_b32_e32 v201, v203
	v_permlane16_swap_b32_e32 v204, v206
	v_permlane16_swap_b32_e32 v205, v207
	v_and_b32_e32 v162, 0xffff0000, v200
	v_lshlrev_b32_e32 v200, 16, v200
	v_and_b32_e32 v163, 0xffff0000, v201
	v_lshlrev_b32_e32 v201, 16, v201
	v_add_f32_e32 v16, v16, v200
	v_add_f32_e32 v17, v17, v162
	v_add_f32_e32 v18, v18, v201
	v_add_f32_e32 v19, v19, v163
	v_mul_f32_e32 v200, v17, v17
	v_mul_f32_e32 v201, v19, v19
	v_fmac_f32_e32 v200, v16, v16
	v_fmac_f32_e32 v201, v18, v18
	v_add_f32_e32 v200, v200, v201
	v_mov_b32_e32 v172, v200
	v_cvt_pk_bf16_f32 v16, v16, v17
	v_cvt_pk_bf16_f32 v17, v18, v19
	v_and_b32_e32 v162, 0xffff0000, v202
	v_lshlrev_b32_e32 v202, 16, v202
	v_and_b32_e32 v163, 0xffff0000, v203
	v_lshlrev_b32_e32 v203, 16, v203
	v_add_f32_e32 v8, v8, v202
	v_add_f32_e32 v9, v9, v162
	v_add_f32_e32 v10, v10, v203
	v_add_f32_e32 v11, v11, v163
	v_mul_f32_e32 v202, v9, v9
	v_mul_f32_e32 v203, v11, v11
	v_fmac_f32_e32 v202, v8, v8
	v_fmac_f32_e32 v203, v10, v10
	v_add_f32_e32 v202, v202, v203
	v_add_f32_e32 v172, v172, v202
	v_cvt_pk_bf16_f32 v18, v8, v9
	v_cvt_pk_bf16_f32 v19, v10, v11
	v_and_b32_e32 v162, 0xffff0000, v204
	v_lshlrev_b32_e32 v204, 16, v204
	v_and_b32_e32 v163, 0xffff0000, v205
	v_lshlrev_b32_e32 v205, 16, v205
	v_add_f32_e32 v4, v4, v204
	v_add_f32_e32 v5, v5, v162
	v_add_f32_e32 v6, v6, v205
	v_add_f32_e32 v7, v7, v163
	v_mul_f32_e32 v204, v5, v5
	v_mul_f32_e32 v205, v7, v7
	v_fmac_f32_e32 v204, v4, v4
	v_fmac_f32_e32 v205, v6, v6
	v_add_f32_e32 v204, v204, v205
	v_add_f32_e32 v172, v172, v204
	v_cvt_pk_bf16_f32 v4, v4, v5
	v_cvt_pk_bf16_f32 v5, v6, v7
	v_and_b32_e32 v162, 0xffff0000, v206
	v_lshlrev_b32_e32 v206, 16, v206
	v_and_b32_e32 v163, 0xffff0000, v207
	v_lshlrev_b32_e32 v207, 16, v207
	v_add_f32_e32 v0, v0, v206
	v_add_f32_e32 v1, v1, v162
	v_add_f32_e32 v2, v2, v207
	v_add_f32_e32 v3, v3, v163
	v_mul_f32_e32 v206, v1, v1
	v_mul_f32_e32 v207, v3, v3
	v_fmac_f32_e32 v206, v0, v0
	v_fmac_f32_e32 v207, v2, v2
	v_add_f32_e32 v206, v206, v207
	v_add_f32_e32 v172, v172, v206
	v_cvt_pk_bf16_f32 v6, v0, v1
	v_cvt_pk_bf16_f32 v7, v2, v3
	v_mov_b32_e32 v8, v172
	v_add_u32_e32 v161, 0x18000, v174
	s_nop 1
	v_permlane16_swap_b32_e32 v16, v18
	v_permlane16_swap_b32_e32 v17, v19
	v_permlane16_swap_b32_e32 v4, v6
	v_permlane16_swap_b32_e32 v5, v7
	global_store_dwordx4 v161, v[16:19], s[18:19]
	global_store_dwordx4 v161, v[4:7], s[18:19] offset:256
	s_waitcnt vmcnt(14)
; __device__ __forceinline__ unsigned cvt_pk_bf16(float lo, float hi) { unsigned r; asm volatile("v_cvt_pk_bf16_f32 %0, %1, %2" : "=v"(r) : "v"(lo), "v"(hi)); return r; }
;     __device__ __forceinline__ void operator()(const f32x4 (&acc)[2][2][4][2], const pg8::Unit& u, int wr, int wc, int fr, int fq) const {
;     ...
;                     for (int bj = 0; bj < 2; ++bj)
; #pragma unroll
;                         for (int n = 0; n < 2; ++n) { const int col = col0 + bj * 128 + n * 16; f32x4 r;
;                             if (RESB) { const u32x2 rw = *(const u32x2*)(resb + (size_t)row * DM + col); r = (f32x4){bf2f(rw.x & 0xffff), bf2f(rw.x >> 16), bf2f(rw.y & 0xffff), bf2f(rw.y >> 16)}; }
;                             else r = *(const f32x4*)(rp + col);
;                             const f32x4 v = r + acc[ai][bj][m][n] * scale;
;                             if (OUTF) *(f32x4*)(out + (size_t)row * DM + col) = v;
;                             else { u32x2 w; w.x = cvt_pk_bf16(v[0], v[1]); w.y = cvt_pk_bf16(v[2], v[3]); *(u32x2*)(outb + (size_t)row * DM + col) = w;
;                                 s += (v[0] * v[0] + v[1] * v[1]) + (v[2] * v[2] + v[3] * v[3]); } }
	v_permlane16_swap_b32_e32 v208, v210
	v_permlane16_swap_b32_e32 v209, v211
	v_permlane16_swap_b32_e32 v212, v214
	v_permlane16_swap_b32_e32 v213, v215
	v_and_b32_e32 v162, 0xffff0000, v208
	v_lshlrev_b32_e32 v208, 16, v208
	v_and_b32_e32 v163, 0xffff0000, v209
	v_lshlrev_b32_e32 v209, 16, v209
	v_add_f32_e32 v124, v124, v208
	v_add_f32_e32 v125, v125, v162
	v_add_f32_e32 v126, v126, v209
	v_add_f32_e32 v127, v127, v163
	v_mul_f32_e32 v208, v125, v125
	v_mul_f32_e32 v209, v127, v127
	v_fmac_f32_e32 v208, v124, v124
	v_fmac_f32_e32 v209, v126, v126
	v_add_f32_e32 v208, v208, v209
	v_mov_b32_e32 v172, v208
	v_cvt_pk_bf16_f32 v124, v124, v125
	v_cvt_pk_bf16_f32 v125, v126, v127
	v_and_b32_e32 v162, 0xffff0000, v210
	v_lshlrev_b32_e32 v210, 16, v210
	v_and_b32_e32 v163, 0xffff0000, v211
	v_lshlrev_b32_e32 v211, 16, v211
	v_add_f32_e32 v120, v120, v210
	v_add_f32_e32 v121, v121, v162
	v_add_f32_e32 v122, v122, v211
	v_add_f32_e32 v123, v123, v163
	v_mul_f32_e32 v210, v121, v121
	v_mul_f32_e32 v211, v123, v123
	v_fmac_f32_e32 v210, v120, v120
	v_fmac_f32_e32 v211, v122, v122
	v_add_f32_e32 v210, v210, v211
	v_add_f32_e32 v172, v172, v210
	v_cvt_pk_bf16_f32 v126, v120, v121
	v_cvt_pk_bf16_f32 v127, v122, v123
	v_and_b32_e32 v162, 0xffff0000, v212
	v_lshlrev_b32_e32 v212, 16, v212
	v_and_b32_e32 v163, 0xffff0000, v213
	v_lshlrev_b32_e32 v213, 16, v213
	v_add_f32_e32 v116, v116, v212
	v_add_f32_e32 v117, v117, v162
	v_add_f32_e32 v118, v118, v213
	v_add_f32_e32 v119, v119, v163
	v_mul_f32_e32 v212, v117, v117
	v_mul_f32_e32 v213, v119, v119
	v_fmac_f32_e32 v212, v116, v116
	v_fmac_f32_e32 v213, v118, v118
	v_add_f32_e32 v212, v212, v213
	v_add_f32_e32 v172, v172, v212
	v_cvt_pk_bf16_f32 v116, v116, v117
	v_cvt_pk_bf16_f32 v117, v118, v119
	v_and_b32_e32 v162, 0xffff0000, v214
	v_lshlrev_b32_e32 v214, 16, v214
	v_and_b32_e32 v163, 0xffff0000, v215
	v_lshlrev_b32_e32 v215, 16, v215
	v_add_f32_e32 v112, v112, v214
	v_add_f32_e32 v113, v113, v162
	v_add_f32_e32 v114, v114, v215
	v_add_f32_e32 v115, v115, v163
	v_mul_f32_e32 v214, v113, v113
	v_mul_f32_e32 v215, v115, v115
	v_fmac_f32_e32 v214, v112, v112
	v_fmac_f32_e32 v215, v114, v114
	v_add_f32_e32 v214, v214, v215
	v_add_f32_e32 v172, v172, v214
	v_cvt_pk_bf16_f32 v118, v112, v113
	v_cvt_pk_bf16_f32 v119, v114, v115
	v_mov_b32_e32 v120, v172
	v_add_u32_e32 v161, 0x40000, v174
	s_nop 1
	v_permlane16_swap_b32_e32 v124, v126
	v_permlane16_swap_b32_e32 v125, v127
	v_permlane16_swap_b32_e32 v116, v118
	v_permlane16_swap_b32_e32 v117, v119
	global_store_dwordx4 v161, v[124:127], s[18:19]
	global_store_dwordx4 v161, v[116:119], s[18:19] offset:256
	s_waitcnt vmcnt(14)
	v_permlane16_swap_b32_e32 v144, v146
	v_permlane16_swap_b32_e32 v145, v147
	v_permlane16_swap_b32_e32 v148, v150
	v_permlane16_swap_b32_e32 v149, v151
	v_and_b32_e32 v162, 0xffff0000, v144
	v_lshlrev_b32_e32 v144, 16, v144
	v_and_b32_e32 v163, 0xffff0000, v145
	v_lshlrev_b32_e32 v145, 16, v145
	v_add_f32_e32 v108, v108, v144
	v_add_f32_e32 v109, v109, v162
	v_add_f32_e32 v110, v110, v145
	v_add_f32_e32 v111, v111, v163
	v_mul_f32_e32 v144, v109, v109
	v_mul_f32_e32 v145, v111, v111
	v_fmac_f32_e32 v144, v108, v108
	v_fmac_f32_e32 v145, v110, v110
	v_add_f32_e32 v144, v144, v145
	v_mov_b32_e32 v172, v144
	v_cvt_pk_bf16_f32 v108, v108, v109
	v_cvt_pk_bf16_f32 v109, v110, v111
	v_and_b32_e32 v162, 0xffff0000, v146
	v_lshlrev_b32_e32 v146, 16, v146
	v_and_b32_e32 v163, 0xffff0000, v147
	v_lshlrev_b32_e32 v147, 16, v147
	v_add_f32_e32 v104, v104, v146
	v_add_f32_e32 v105, v105, v162
	v_add_f32_e32 v106, v106, v147
	v_add_f32_e32 v107, v107, v163
	v_mul_f32_e32 v146, v105, v105
	v_mul_f32_e32 v147, v107, v107
	v_fmac_f32_e32 v146, v104, v104
	v_fmac_f32_e32 v147, v106, v106
	v_add_f32_e32 v146, v146, v147
	v_add_f32_e32 v172, v172, v146
	v_cvt_pk_bf16_f32 v110, v104, v105
	v_cvt_pk_bf16_f32 v111, v106, v107
	v_and_b32_e32 v162, 0xffff0000, v148
	v_lshlrev_b32_e32 v148, 16, v148
	v_and_b32_e32 v163, 0xffff0000, v149
	v_lshlrev_b32_e32 v149, 16, v149
	v_add_f32_e32 v100, v100, v148
	v_add_f32_e32 v101, v101, v162
	v_add_f32_e32 v102, v102, v149
	v_add_f32_e32 v103, v103, v163
	v_mul_f32_e32 v148, v101, v101
	v_mul_f32_e32 v149, v103, v103
	v_fmac_f32_e32 v148, v100, v100
	v_fmac_f32_e32 v149, v102, v102
	v_add_f32_e32 v148, v148, v149
	v_add_f32_e32 v172, v172, v148
	v_cvt_pk_bf16_f32 v100, v100, v101
	v_cvt_pk_bf16_f32 v101, v102, v103
	v_and_b32_e32 v162, 0xffff0000, v150
	v_lshlrev_b32_e32 v150, 16, v150
	v_and_b32_e32 v163, 0xffff0000, v151
	v_lshlrev_b32_e32 v151, 16, v151
	v_add_f32_e32 v96, v96, v150
	v_add_f32_e32 v97, v97, v162
	v_add_f32_e32 v98, v98, v151
	v_add_f32_e32 v99, v99, v163
	v_mul_f32_e32 v150, v97, v97
	v_mul_f32_e32 v151, v99, v99
	v_fmac_f32_e32 v150, v96, v96
	v_fmac_f32_e32 v151, v98, v98
	v_add_f32_e32 v150, v150, v151
	v_add_f32_e32 v172, v172, v150
	v_cvt_pk_bf16_f32 v102, v96, v97
	v_cvt_pk_bf16_f32 v103, v98, v99
	v_mov_b32_e32 v104, v172
	v_add_u32_e32 v161, 0x48000, v174
	s_nop 1
	v_permlane16_swap_b32_e32 v108, v110
	v_permlane16_swap_b32_e32 v109, v111
	v_permlane16_swap_b32_e32 v100, v102
	v_permlane16_swap_b32_e32 v101, v103
	global_store_dwordx4 v161, v[108:111], s[18:19]
	global_store_dwordx4 v161, v[100:103], s[18:19] offset:256
	s_waitcnt vmcnt(14)
; __device__ __forceinline__ unsigned cvt_pk_bf16(float lo, float hi) { unsigned r; asm volatile("v_cvt_pk_bf16_f32 %0, %1, %2" : "=v"(r) : "v"(lo), "v"(hi)); return r; }
;     __device__ __forceinline__ void operator()(const f32x4 (&acc)[2][2][4][2], const pg8::Unit& u, int wr, int wc, int fr, int fq) const {
;     ...
;                     for (int bj = 0; bj < 2; ++bj)
; #pragma unroll
;                         for (int n = 0; n < 2; ++n) { const int col = col0 + bj * 128 + n * 16; f32x4 r;
;                             if (RESB) { const u32x2 rw = *(const u32x2*)(resb + (size_t)row * DM + col); r = (f32x4){bf2f(rw.x & 0xffff), bf2f(rw.x >> 16), bf2f(rw.y & 0xffff), bf2f(rw.y >> 16)}; }
;                             else r = *(const f32x4*)(rp + col);
;                             const f32x4 v = r + acc[ai][bj][m][n] * scale;
;                             if (OUTF) *(f32x4*)(out + (size_t)row * DM + col) = v;
;                             else { u32x2 w; w.x = cvt_pk_bf16(v[0], v[1]); w.y = cvt_pk_bf16(v[2], v[3]); *(u32x2*)(outb + (size_t)row * DM + col) = w;
;                                 s += (v[0] * v[0] + v[1] * v[1]) + (v[2] * v[2] + v[3] * v[3]); } }
;                     if (!OUTF) { s += __shfl_xor(s, 16); s += __shfl_xor(s, 32); if (fq == 0) atomicAdd(ss + row, s); }
;                 }
	v_permlane16_swap_b32_e32 v152, v154
	v_permlane16_swap_b32_e32 v153, v155
	v_permlane16_swap_b32_e32 v156, v158
	v_permlane16_swap_b32_e32 v157, v159
	v_and_b32_e32 v162, 0xffff0000, v152
	v_lshlrev_b32_e32 v152, 16, v152
	v_and_b32_e32 v163, 0xffff0000, v153
	v_lshlrev_b32_e32 v153, 16, v153
	v_add_f32_e32 v92, v92, v152
	v_add_f32_e32 v93, v93, v162
	v_add_f32_e32 v94, v94, v153
	v_add_f32_e32 v95, v95, v163
	v_mul_f32_e32 v152, v93, v93
	v_mul_f32_e32 v153, v95, v95
	v_fmac_f32_e32 v152, v92, v92
	v_fmac_f32_e32 v153, v94, v94
	v_add_f32_e32 v152, v152, v153
	v_mov_b32_e32 v172, v152
	v_cvt_pk_bf16_f32 v92, v92, v93
	v_cvt_pk_bf16_f32 v93, v94, v95
	v_and_b32_e32 v162, 0xffff0000, v154
	v_lshlrev_b32_e32 v154, 16, v154
	v_and_b32_e32 v163, 0xffff0000, v155
	v_lshlrev_b32_e32 v155, 16, v155
	v_add_f32_e32 v88, v88, v154
	v_add_f32_e32 v89, v89, v162
	v_add_f32_e32 v90, v90, v155
	v_add_f32_e32 v91, v91, v163
	v_mul_f32_e32 v154, v89, v89
	v_mul_f32_e32 v155, v91, v91
	v_fmac_f32_e32 v154, v88, v88
	v_fmac_f32_e32 v155, v90, v90
	v_add_f32_e32 v154, v154, v155
	v_add_f32_e32 v172, v172, v154
	v_cvt_pk_bf16_f32 v94, v88, v89
	v_cvt_pk_bf16_f32 v95, v90, v91
	v_and_b32_e32 v162, 0xffff0000, v156
	v_lshlrev_b32_e32 v156, 16, v156
	v_and_b32_e32 v163, 0xffff0000, v157
	v_lshlrev_b32_e32 v157, 16, v157
	v_add_f32_e32 v84, v84, v156
	v_add_f32_e32 v85, v85, v162
	v_add_f32_e32 v86, v86, v157
	v_add_f32_e32 v87, v87, v163
	v_mul_f32_e32 v156, v85, v85
	v_mul_f32_e32 v157, v87, v87
	v_fmac_f32_e32 v156, v84, v84
	v_fmac_f32_e32 v157, v86, v86
	v_add_f32_e32 v156, v156, v157
	v_add_f32_e32 v172, v172, v156
	v_cvt_pk_bf16_f32 v84, v84, v85
	v_cvt_pk_bf16_f32 v85, v86, v87
	v_and_b32_e32 v162, 0xffff0000, v158
	v_lshlrev_b32_e32 v158, 16, v158
	v_and_b32_e32 v163, 0xffff0000, v159
	v_lshlrev_b32_e32 v159, 16, v159
	v_add_f32_e32 v80, v80, v158
	v_add_f32_e32 v81, v81, v162
	v_add_f32_e32 v82, v82, v159
	v_add_f32_e32 v83, v83, v163
	v_mul_f32_e32 v158, v81, v81
	v_mul_f32_e32 v159, v83, v83
	v_fmac_f32_e32 v158, v80, v80
	v_fmac_f32_e32 v159, v82, v82
	v_add_f32_e32 v158, v158, v159
	v_add_f32_e32 v172, v172, v158
	v_cvt_pk_bf16_f32 v86, v80, v81
	v_cvt_pk_bf16_f32 v87, v82, v83
	v_mov_b32_e32 v88, v172
	v_add_u32_e32 v161, 0x50000, v174
	s_nop 1
	v_permlane16_swap_b32_e32 v92, v94
	v_permlane16_swap_b32_e32 v93, v95
	v_permlane16_swap_b32_e32 v84, v86
	v_permlane16_swap_b32_e32 v85, v87
	global_store_dwordx4 v161, v[92:95], s[18:19]
	global_store_dwordx4 v161, v[84:87], s[18:19] offset:256
	s_waitcnt vmcnt(14)
	v_permlane16_swap_b32_e32 v176, v178
	v_permlane16_swap_b32_e32 v177, v179
	v_permlane16_swap_b32_e32 v180, v182
	v_permlane16_swap_b32_e32 v181, v183
	v_and_b32_e32 v162, 0xffff0000, v176
	v_lshlrev_b32_e32 v176, 16, v176
	v_and_b32_e32 v163, 0xffff0000, v177
	v_lshlrev_b32_e32 v177, 16, v177
	v_add_f32_e32 v76, v76, v176
	v_add_f32_e32 v77, v77, v162
	v_add_f32_e32 v78, v78, v177
	v_add_f32_e32 v79, v79, v163
	v_mul_f32_e32 v176, v77, v77
	v_mul_f32_e32 v177, v79, v79
	v_fmac_f32_e32 v176, v76, v76
	v_fmac_f32_e32 v177, v78, v78
	v_add_f32_e32 v176, v176, v177
	v_mov_b32_e32 v172, v176
	v_cvt_pk_bf16_f32 v76, v76, v77
	v_cvt_pk_bf16_f32 v77, v78, v79
	v_and_b32_e32 v162, 0xffff0000, v178
	v_lshlrev_b32_e32 v178, 16, v178
	v_and_b32_e32 v163, 0xffff0000, v179
	v_lshlrev_b32_e32 v179, 16, v179
	v_add_f32_e32 v72, v72, v178
	v_add_f32_e32 v73, v73, v162
	v_add_f32_e32 v74, v74, v179
	v_add_f32_e32 v75, v75, v163
	v_mul_f32_e32 v178, v73, v73
	v_mul_f32_e32 v179, v75, v75
	v_fmac_f32_e32 v178, v72, v72
	v_fmac_f32_e32 v179, v74, v74
	v_add_f32_e32 v178, v178, v179
	v_add_f32_e32 v172, v172, v178
	v_cvt_pk_bf16_f32 v78, v72, v73
	v_cvt_pk_bf16_f32 v79, v74, v75
	v_and_b32_e32 v162, 0xffff0000, v180
	v_lshlrev_b32_e32 v180, 16, v180
	v_and_b32_e32 v163, 0xffff0000, v181
	v_lshlrev_b32_e32 v181, 16, v181
	v_add_f32_e32 v68, v68, v180
	v_add_f32_e32 v69, v69, v162
	v_add_f32_e32 v70, v70, v181
	v_add_f32_e32 v71, v71, v163
	v_mul_f32_e32 v180, v69, v69
	v_mul_f32_e32 v181, v71, v71
	v_fmac_f32_e32 v180, v68, v68
	v_fmac_f32_e32 v181, v70, v70
	v_add_f32_e32 v180, v180, v181
	v_add_f32_e32 v172, v172, v180
	v_cvt_pk_bf16_f32 v68, v68, v69
	v_cvt_pk_bf16_f32 v69, v70, v71
	v_and_b32_e32 v162, 0xffff0000, v182
	v_lshlrev_b32_e32 v182, 16, v182
	v_and_b32_e32 v163, 0xffff0000, v183
	v_lshlrev_b32_e32 v183, 16, v183
	v_add_f32_e32 v56, v56, v182
	v_add_f32_e32 v57, v57, v162
	v_add_f32_e32 v58, v58, v183
	v_add_f32_e32 v59, v59, v163
	v_mul_f32_e32 v182, v57, v57
	v_mul_f32_e32 v183, v59, v59
	v_fmac_f32_e32 v182, v56, v56
	v_fmac_f32_e32 v183, v58, v58
	v_add_f32_e32 v182, v182, v183
	v_add_f32_e32 v172, v172, v182
	v_cvt_pk_bf16_f32 v70, v56, v57
	v_cvt_pk_bf16_f32 v71, v58, v59
	v_mov_b32_e32 v72, v172
	v_add_u32_e32 v161, 0x58000, v174
	s_nop 1
	v_permlane16_swap_b32_e32 v76, v78
	v_permlane16_swap_b32_e32 v77, v79
	v_permlane16_swap_b32_e32 v68, v70
	v_permlane16_swap_b32_e32 v69, v71
	global_store_dwordx4 v161, v[76:79], s[18:19]
	global_store_dwordx4 v161, v[68:71], s[18:19] offset:256
	v_xor_b32_e32 v173, 16, v170
	v_lshlrev_b32_e32 v173, 2, v173
	ds_bpermute_b32 v61, v173, v60
	ds_bpermute_b32 v41, v173, v40
	ds_bpermute_b32 v25, v173, v24
	ds_bpermute_b32 v9, v173, v8
	ds_bpermute_b32 v121, v173, v120
	ds_bpermute_b32 v105, v173, v104
	ds_bpermute_b32 v89, v173, v88
	ds_bpermute_b32 v73, v173, v72
	s_waitcnt lgkmcnt(0)
	v_add_f32_e32 v60, v60, v61
	v_add_f32_e32 v40, v40, v41
	v_add_f32_e32 v24, v24, v25
	v_add_f32_e32 v8, v8, v9
	v_add_f32_e32 v120, v120, v121
	v_add_f32_e32 v104, v104, v105
	v_add_f32_e32 v88, v88, v89
	v_add_f32_e32 v72, v72, v73
	v_xor_b32_e32 v173, 32, v170
	v_lshlrev_b32_e32 v173, 2, v173
	ds_bpermute_b32 v61, v173, v60
	ds_bpermute_b32 v41, v173, v40
	ds_bpermute_b32 v25, v173, v24
	ds_bpermute_b32 v9, v173, v8
	ds_bpermute_b32 v121, v173, v120
	ds_bpermute_b32 v105, v173, v104
	ds_bpermute_b32 v89, v173, v88
	ds_bpermute_b32 v73, v173, v72
	s_waitcnt lgkmcnt(0)
	v_add_f32_e32 v60, v60, v61
	v_add_f32_e32 v40, v40, v41
	v_add_f32_e32 v24, v24, v25
	v_add_f32_e32 v8, v8, v9
	v_add_f32_e32 v120, v120, v121
	v_add_f32_e32 v104, v104, v105
	v_add_f32_e32 v88, v88, v89
	v_add_f32_e32 v72, v72, v73
	v_lshl_add_u32 v160, s46, 8, v164
	v_lshlrev_b32_e32 v160, 2, v160
	s_and_saveexec_b64 s[0:1], s[8:9]
	global_atomic_add_f32 v160, v60, s[20:21]
	global_atomic_add_f32 v160, v40, s[20:21] offset:64
	global_atomic_add_f32 v160, v24, s[20:21] offset:128
	global_atomic_add_f32 v160, v8, s[20:21] offset:192
	global_atomic_add_f32 v160, v120, s[20:21] offset:512
	global_atomic_add_f32 v160, v104, s[20:21] offset:576
	global_atomic_add_f32 v160, v88, s[20:21] offset:640
	global_atomic_add_f32 v160, v72, s[20:21] offset:704
	s_or_b64 exec, exec, s[0:1]
	s_branch .Lp7e_done

;     __device__ __forceinline__ void operator()(const f32x4 (&acc)[2][2][4][2], const pg8::Unit& u, int wr, int wc, int fr, int fq) const {
;     ...
;             for (int m = 0; m < 4; ++m) { const int row = row0 + ai * 128 + m * 16;
;                 if (row < MV) {
;                     const float* rp = (row < MPR) ? res_p + (size_t)row * DM : res_s + (size_t)(row - MPR) * DM;
;                     float s = 0.f;
; #pragma unroll
;                     for (int bj = 0; bj < 2; ++bj)
; #pragma unroll
;                         for (int n = 0; n < 2; ++n) { const int col = col0 + bj * 128 + n * 16; f32x4 r;
;                             if (RESB) { const u32x2 rw = *(const u32x2*)(resb + (size_t)row * DM + col); r = (f32x4){bf2f(rw.x & 0xffff), bf2f(rw.x >> 16), bf2f(rw.y & 0xffff), bf2f(rw.y >> 16)}; }
;                             else r = *(const f32x4*)(rp + col);
;                             const f32x4 v = r + acc[ai][bj][m][n] * scale;
;                             if (OUTF) *(f32x4*)(out + (size_t)row * DM + col) = v;
.LBB0_1294:
	s_cmp_lt_i32 s94, 2
	s_cbranch_scc0 .LBB0_1305
	v_lshl_add_u32 v190, s93, 8, v230
	v_lshl_or_b32 v191, s48, 8, v232
	v_lshlrev_b32_e32 v190, 11, v190
	v_lshl_add_u32 v190, v191, 1, v190
	v_lshlrev_b32_e32 v191, 1, v190
	v_and_b32_e32 v196, 4, v232
	v_mul_u32_u24_e32 v196, 6, v196
	v_add_u32_e32 v196, v196, v190
	global_load_dwordx4 v[134:137], v196, s[18:19]
	global_load_dwordx4 v[138:141], v196, s[18:19] offset:256
	v_add_u32_e32 v192, 0x8000, v196
	global_load_dwordx4 v[142:145], v192, s[18:19]
	global_load_dwordx4 v[146:149], v192, s[18:19] offset:256
	v_add_u32_e32 v192, 0x10000, v196
	global_load_dwordx4 v[150:153], v192, s[18:19]
	global_load_dwordx4 v[154:157], v192, s[18:19] offset:256
	v_add_u32_e32 v192, 0x18000, v196
	global_load_dwordx4 v[158:161], v192, s[18:19]
	global_load_dwordx4 v[162:165], v192, s[18:19] offset:256
	v_add_u32_e32 v192, 0x40000, v196
	global_load_dwordx4 v[166:169], v192, s[18:19]
	global_load_dwordx4 v[170:173], v192, s[18:19] offset:256
	v_add_u32_e32 v192, 0x48000, v196
	global_load_dwordx4 v[174:177], v192, s[18:19]
	global_load_dwordx4 v[178:181], v192, s[18:19] offset:256
	v_add_u32_e32 v192, 0x50000, v196
	global_load_dwordx4 v[182:185], v192, s[18:19]
	global_load_dwordx4 v[186:189], v192, s[18:19] offset:256
	s_waitcnt vmcnt(12)
	v_permlane16_swap_b32_e32 v134, v136
	v_permlane16_swap_b32_e32 v135, v137
	v_permlane16_swap_b32_e32 v138, v140
	v_permlane16_swap_b32_e32 v139, v141
	v_and_b32_e32 v194, 0xffff0000, v134
	v_lshlrev_b32_e32 v134, 16, v134
	v_and_b32_e32 v195, 0xffff0000, v135
	v_lshlrev_b32_e32 v135, 16, v135
	v_fma_f32 v90, v90, 0.5, v134
	v_fma_f32 v91, v91, 0.5, v194
	v_fma_f32 v92, v92, 0.5, v135
	v_fma_f32 v93, v93, 0.5, v195
	v_and_b32_e32 v194, 0xffff0000, v136
	v_lshlrev_b32_e32 v136, 16, v136
	v_and_b32_e32 v195, 0xffff0000, v137
	v_lshlrev_b32_e32 v137, 16, v137
	v_fma_f32 v82, v82, 0.5, v136
	v_fma_f32 v83, v83, 0.5, v194
	v_fma_f32 v84, v84, 0.5, v137
	v_fma_f32 v85, v85, 0.5, v195
	v_and_b32_e32 v194, 0xffff0000, v138
	v_lshlrev_b32_e32 v138, 16, v138
	v_and_b32_e32 v195, 0xffff0000, v139
	v_lshlrev_b32_e32 v139, 16, v139
	v_fma_f32 v70, v70, 0.5, v138
	v_fma_f32 v71, v71, 0.5, v194
	v_fma_f32 v72, v72, 0.5, v139
	v_fma_f32 v73, v73, 0.5, v195
	v_and_b32_e32 v194, 0xffff0000, v140
	v_lshlrev_b32_e32 v140, 16, v140
	v_and_b32_e32 v195, 0xffff0000, v141
	v_lshlrev_b32_e32 v141, 16, v141
	v_fma_f32 v58, v58, 0.5, v140
	v_fma_f32 v59, v59, 0.5, v194
	v_fma_f32 v60, v60, 0.5, v141
	v_fma_f32 v61, v61, 0.5, v195
	v_add_u32_e32 v192, 0x58000, v196
	global_load_dwordx4 v[134:137], v192, s[18:19]
	global_load_dwordx4 v[138:141], v192, s[18:19] offset:256
	global_store_dwordx4 v191, v[90:93], s[12:13]
	global_store_dwordx4 v191, v[82:85], s[12:13] offset:64
	global_store_dwordx4 v191, v[70:73], s[12:13] offset:512
	global_store_dwordx4 v191, v[58:61], s[12:13] offset:576
	s_waitcnt vmcnt(16)
	v_permlane16_swap_b32_e32 v142, v144
	v_permlane16_swap_b32_e32 v143, v145
	v_permlane16_swap_b32_e32 v146, v148
	v_permlane16_swap_b32_e32 v147, v149
	v_and_b32_e32 v194, 0xffff0000, v142
	v_lshlrev_b32_e32 v142, 16, v142
	v_and_b32_e32 v195, 0xffff0000, v143
	v_lshlrev_b32_e32 v143, 16, v143
	v_fma_f32 v66, v66, 0.5, v142
	v_fma_f32 v67, v67, 0.5, v194
	v_fma_f32 v68, v68, 0.5, v143
	v_fma_f32 v69, v69, 0.5, v195
	v_and_b32_e32 v194, 0xffff0000, v144
	v_lshlrev_b32_e32 v144, 16, v144
	v_and_b32_e32 v195, 0xffff0000, v145
	v_lshlrev_b32_e32 v145, 16, v145
	v_fma_f32 v54, v54, 0.5, v144
	v_fma_f32 v55, v55, 0.5, v194
	v_fma_f32 v56, v56, 0.5, v145
	v_fma_f32 v57, v57, 0.5, v195
	v_and_b32_e32 v194, 0xffff0000, v146
	v_lshlrev_b32_e32 v146, 16, v146
	v_and_b32_e32 v195, 0xffff0000, v147
	v_lshlrev_b32_e32 v147, 16, v147
	v_fma_f32 v46, v46, 0.5, v146
	v_fma_f32 v47, v47, 0.5, v194
	v_fma_f32 v48, v48, 0.5, v147
	v_fma_f32 v49, v49, 0.5, v195
	v_and_b32_e32 v194, 0xffff0000, v148
	v_lshlrev_b32_e32 v148, 16, v148
	v_and_b32_e32 v195, 0xffff0000, v149
	v_lshlrev_b32_e32 v149, 16, v149
	v_fma_f32 v38, v38, 0.5, v148
	v_fma_f32 v39, v39, 0.5, v194
	v_fma_f32 v40, v40, 0.5, v149
	v_fma_f32 v41, v41, 0.5, v195
	v_add_u32_e32 v193, 0x10000, v191
	global_store_dwordx4 v193, v[66:69], s[12:13]
	global_store_dwordx4 v193, v[54:57], s[12:13] offset:64
	global_store_dwordx4 v193, v[46:49], s[12:13] offset:512
	global_store_dwordx4 v193, v[38:41], s[12:13] offset:576
	s_waitcnt vmcnt(18)
	v_permlane16_swap_b32_e32 v150, v152
	v_permlane16_swap_b32_e32 v151, v153
	v_permlane16_swap_b32_e32 v154, v156
	v_permlane16_swap_b32_e32 v155, v157
	v_and_b32_e32 v194, 0xffff0000, v150
	v_lshlrev_b32_e32 v150, 16, v150
	v_and_b32_e32 v195, 0xffff0000, v151
	v_lshlrev_b32_e32 v151, 16, v151
	v_fma_f32 v42, v42, 0.5, v150
	v_fma_f32 v43, v43, 0.5, v194
	v_fma_f32 v44, v44, 0.5, v151
	v_fma_f32 v45, v45, 0.5, v195
	v_and_b32_e32 v194, 0xffff0000, v152
	v_lshlrev_b32_e32 v152, 16, v152
	v_and_b32_e32 v195, 0xffff0000, v153
	v_lshlrev_b32_e32 v153, 16, v153
	v_fma_f32 v30, v30, 0.5, v152
	v_fma_f32 v31, v31, 0.5, v194
	v_fma_f32 v32, v32, 0.5, v153
	v_fma_f32 v33, v33, 0.5, v195
	v_and_b32_e32 v194, 0xffff0000, v154
	v_lshlrev_b32_e32 v154, 16, v154
	v_and_b32_e32 v195, 0xffff0000, v155
	v_lshlrev_b32_e32 v155, 16, v155
	v_fma_f32 v26, v26, 0.5, v154
	v_fma_f32 v27, v27, 0.5, v194
	v_fma_f32 v28, v28, 0.5, v155
	v_fma_f32 v29, v29, 0.5, v195
	v_and_b32_e32 v194, 0xffff0000, v156
	v_lshlrev_b32_e32 v156, 16, v156
	v_and_b32_e32 v195, 0xffff0000, v157
	v_lshlrev_b32_e32 v157, 16, v157
	v_fma_f32 v18, v18, 0.5, v156
	v_fma_f32 v19, v19, 0.5, v194
	v_fma_f32 v20, v20, 0.5, v157
	v_fma_f32 v21, v21, 0.5, v195
	v_add_u32_e32 v193, 0x20000, v191
	global_store_dwordx4 v193, v[42:45], s[12:13]
	global_store_dwordx4 v193, v[30:33], s[12:13] offset:64
	global_store_dwordx4 v193, v[26:29], s[12:13] offset:512
	global_store_dwordx4 v193, v[18:21], s[12:13] offset:576
	s_waitcnt vmcnt(20)
;     __device__ __forceinline__ void operator()(const f32x4 (&acc)[2][2][4][2], const pg8::Unit& u, int wr, int wc, int fr, int fq) const {
;     ...
;                     for (int bj = 0; bj < 2; ++bj)
; #pragma unroll
;                         for (int n = 0; n < 2; ++n) { const int col = col0 + bj * 128 + n * 16; f32x4 r;
;                             if (RESB) { const u32x2 rw = *(const u32x2*)(resb + (size_t)row * DM + col); r = (f32x4){bf2f(rw.x & 0xffff), bf2f(rw.x >> 16), bf2f(rw.y & 0xffff), bf2f(rw.y >> 16)}; }
;                             else r = *(const f32x4*)(rp + col);
;                             const f32x4 v = r + acc[ai][bj][m][n] * scale;
;                             if (OUTF) *(f32x4*)(out + (size_t)row * DM + col) = v;
	v_permlane16_swap_b32_e32 v158, v160
	v_permlane16_swap_b32_e32 v159, v161
	v_permlane16_swap_b32_e32 v162, v164
	v_permlane16_swap_b32_e32 v163, v165
	v_and_b32_e32 v194, 0xffff0000, v158
	v_lshlrev_b32_e32 v158, 16, v158
	v_and_b32_e32 v195, 0xffff0000, v159
	v_lshlrev_b32_e32 v159, 16, v159
	v_fma_f32 v22, v22, 0.5, v158
	v_fma_f32 v23, v23, 0.5, v194
	v_fma_f32 v24, v24, 0.5, v159
	v_fma_f32 v25, v25, 0.5, v195
	v_and_b32_e32 v194, 0xffff0000, v160
	v_lshlrev_b32_e32 v160, 16, v160
	v_and_b32_e32 v195, 0xffff0000, v161
	v_lshlrev_b32_e32 v161, 16, v161
	v_fma_f32 v14, v14, 0.5, v160
	v_fma_f32 v15, v15, 0.5, v194
	v_fma_f32 v16, v16, 0.5, v161
	v_fma_f32 v17, v17, 0.5, v195
	v_and_b32_e32 v194, 0xffff0000, v162
	v_lshlrev_b32_e32 v162, 16, v162
	v_and_b32_e32 v195, 0xffff0000, v163
	v_lshlrev_b32_e32 v163, 16, v163
	v_fma_f32 v10, v10, 0.5, v162
	v_fma_f32 v11, v11, 0.5, v194
	v_fma_f32 v12, v12, 0.5, v163
	v_fma_f32 v13, v13, 0.5, v195
	v_and_b32_e32 v194, 0xffff0000, v164
	v_lshlrev_b32_e32 v164, 16, v164
	v_and_b32_e32 v195, 0xffff0000, v165
	v_lshlrev_b32_e32 v165, 16, v165
	v_fma_f32 v6, v6, 0.5, v164
	v_fma_f32 v7, v7, 0.5, v194
	v_fma_f32 v8, v8, 0.5, v165
	v_fma_f32 v9, v9, 0.5, v195
	v_add_u32_e32 v193, 0x30000, v191
	global_store_dwordx4 v193, v[22:25], s[12:13]
	global_store_dwordx4 v193, v[14:17], s[12:13] offset:64
	global_store_dwordx4 v193, v[10:13], s[12:13] offset:512
	global_store_dwordx4 v193, v[6:9], s[12:13] offset:576
	s_waitcnt vmcnt(22)
	v_permlane16_swap_b32_e32 v166, v168
	v_permlane16_swap_b32_e32 v167, v169
	v_permlane16_swap_b32_e32 v170, v172
	v_permlane16_swap_b32_e32 v171, v173
	v_and_b32_e32 v194, 0xffff0000, v166
	v_lshlrev_b32_e32 v166, 16, v166
	v_and_b32_e32 v195, 0xffff0000, v167
	v_lshlrev_b32_e32 v167, 16, v167
	v_fma_f32 v130, v130, 0.5, v166
	v_fma_f32 v131, v131, 0.5, v194
	v_fma_f32 v132, v132, 0.5, v167
	v_fma_f32 v133, v133, 0.5, v195
	v_and_b32_e32 v194, 0xffff0000, v168
	v_lshlrev_b32_e32 v168, 16, v168
	v_and_b32_e32 v195, 0xffff0000, v169
	v_lshlrev_b32_e32 v169, 16, v169
	v_fma_f32 v126, v126, 0.5, v168
	v_fma_f32 v127, v127, 0.5, v194
	v_fma_f32 v128, v128, 0.5, v169
	v_fma_f32 v129, v129, 0.5, v195
	v_and_b32_e32 v194, 0xffff0000, v170
	v_lshlrev_b32_e32 v170, 16, v170
	v_and_b32_e32 v195, 0xffff0000, v171
	v_lshlrev_b32_e32 v171, 16, v171
	v_fma_f32 v122, v122, 0.5, v170
	v_fma_f32 v123, v123, 0.5, v194
	v_fma_f32 v124, v124, 0.5, v171
	v_fma_f32 v125, v125, 0.5, v195
	v_and_b32_e32 v194, 0xffff0000, v172
	v_lshlrev_b32_e32 v172, 16, v172
	v_and_b32_e32 v195, 0xffff0000, v173
	v_lshlrev_b32_e32 v173, 16, v173
	v_fma_f32 v118, v118, 0.5, v172
	v_fma_f32 v119, v119, 0.5, v194
	v_fma_f32 v120, v120, 0.5, v173
	v_fma_f32 v121, v121, 0.5, v195
	v_add_u32_e32 v193, 0x80000, v191
	global_store_dwordx4 v193, v[130:133], s[12:13]
	global_store_dwordx4 v193, v[126:129], s[12:13] offset:64
	global_store_dwordx4 v193, v[122:125], s[12:13] offset:512
	global_store_dwordx4 v193, v[118:121], s[12:13] offset:576
	s_waitcnt vmcnt(24)
;     __device__ __forceinline__ void operator()(const f32x4 (&acc)[2][2][4][2], const pg8::Unit& u, int wr, int wc, int fr, int fq) const {
;     ...
;                     for (int bj = 0; bj < 2; ++bj)
; #pragma unroll
;                         for (int n = 0; n < 2; ++n) { const int col = col0 + bj * 128 + n * 16; f32x4 r;
;                             if (RESB) { const u32x2 rw = *(const u32x2*)(resb + (size_t)row * DM + col); r = (f32x4){bf2f(rw.x & 0xffff), bf2f(rw.x >> 16), bf2f(rw.y & 0xffff), bf2f(rw.y >> 16)}; }
;                             else r = *(const f32x4*)(rp + col);
;                             const f32x4 v = r + acc[ai][bj][m][n] * scale;
;                             if (OUTF) *(f32x4*)(out + (size_t)row * DM + col) = v;
	v_permlane16_swap_b32_e32 v174, v176
	v_permlane16_swap_b32_e32 v175, v177
	v_permlane16_swap_b32_e32 v178, v180
	v_permlane16_swap_b32_e32 v179, v181
	v_and_b32_e32 v194, 0xffff0000, v174
	v_lshlrev_b32_e32 v174, 16, v174
	v_and_b32_e32 v195, 0xffff0000, v175
	v_lshlrev_b32_e32 v175, 16, v175
	v_fma_f32 v114, v114, 0.5, v174
	v_fma_f32 v115, v115, 0.5, v194
	v_fma_f32 v116, v116, 0.5, v175
	v_fma_f32 v117, v117, 0.5, v195
	v_and_b32_e32 v194, 0xffff0000, v176
	v_lshlrev_b32_e32 v176, 16, v176
	v_and_b32_e32 v195, 0xffff0000, v177
	v_lshlrev_b32_e32 v177, 16, v177
	v_fma_f32 v110, v110, 0.5, v176
	v_fma_f32 v111, v111, 0.5, v194
	v_fma_f32 v112, v112, 0.5, v177
	v_fma_f32 v113, v113, 0.5, v195
	v_and_b32_e32 v194, 0xffff0000, v178
	v_lshlrev_b32_e32 v178, 16, v178
	v_and_b32_e32 v195, 0xffff0000, v179
	v_lshlrev_b32_e32 v179, 16, v179
	v_fma_f32 v106, v106, 0.5, v178
	v_fma_f32 v107, v107, 0.5, v194
	v_fma_f32 v108, v108, 0.5, v179
	v_fma_f32 v109, v109, 0.5, v195
	v_and_b32_e32 v194, 0xffff0000, v180
	v_lshlrev_b32_e32 v180, 16, v180
	v_and_b32_e32 v195, 0xffff0000, v181
	v_lshlrev_b32_e32 v181, 16, v181
	v_fma_f32 v102, v102, 0.5, v180
	v_fma_f32 v103, v103, 0.5, v194
	v_fma_f32 v104, v104, 0.5, v181
	v_fma_f32 v105, v105, 0.5, v195
	v_add_u32_e32 v193, 0x90000, v191
	global_store_dwordx4 v193, v[114:117], s[12:13]
	global_store_dwordx4 v193, v[110:113], s[12:13] offset:64
	global_store_dwordx4 v193, v[106:109], s[12:13] offset:512
	global_store_dwordx4 v193, v[102:105], s[12:13] offset:576
	s_waitcnt vmcnt(26)
	v_permlane16_swap_b32_e32 v182, v184
	v_permlane16_swap_b32_e32 v183, v185
	v_permlane16_swap_b32_e32 v186, v188
	v_permlane16_swap_b32_e32 v187, v189
	v_and_b32_e32 v194, 0xffff0000, v182
	v_lshlrev_b32_e32 v182, 16, v182
	v_and_b32_e32 v195, 0xffff0000, v183
	v_lshlrev_b32_e32 v183, 16, v183
	v_fma_f32 v98, v98, 0.5, v182
	v_fma_f32 v99, v99, 0.5, v194
	v_fma_f32 v100, v100, 0.5, v183
	v_fma_f32 v101, v101, 0.5, v195
	v_and_b32_e32 v194, 0xffff0000, v184
	v_lshlrev_b32_e32 v184, 16, v184
	v_and_b32_e32 v195, 0xffff0000, v185
	v_lshlrev_b32_e32 v185, 16, v185
	v_fma_f32 v94, v94, 0.5, v184
	v_fma_f32 v95, v95, 0.5, v194
	v_fma_f32 v96, v96, 0.5, v185
	v_fma_f32 v97, v97, 0.5, v195
	v_and_b32_e32 v194, 0xffff0000, v186
	v_lshlrev_b32_e32 v186, 16, v186
	v_and_b32_e32 v195, 0xffff0000, v187
	v_lshlrev_b32_e32 v187, 16, v187
	v_fma_f32 v86, v86, 0.5, v186
	v_fma_f32 v87, v87, 0.5, v194
	v_fma_f32 v88, v88, 0.5, v187
	v_fma_f32 v89, v89, 0.5, v195
	v_and_b32_e32 v194, 0xffff0000, v188
	v_lshlrev_b32_e32 v188, 16, v188
	v_and_b32_e32 v195, 0xffff0000, v189
	v_lshlrev_b32_e32 v189, 16, v189
	v_fma_f32 v78, v78, 0.5, v188
	v_fma_f32 v79, v79, 0.5, v194
	v_fma_f32 v80, v80, 0.5, v189
	v_fma_f32 v81, v81, 0.5, v195
	v_add_u32_e32 v193, 0xa0000, v191
	global_store_dwordx4 v193, v[98:101], s[12:13]
	global_store_dwordx4 v193, v[94:97], s[12:13] offset:64
	global_store_dwordx4 v193, v[86:89], s[12:13] offset:512
	global_store_dwordx4 v193, v[78:81], s[12:13] offset:576
	s_waitcnt vmcnt(28)
	v_permlane16_swap_b32_e32 v134, v136
	v_permlane16_swap_b32_e32 v135, v137
	v_permlane16_swap_b32_e32 v138, v140
	v_permlane16_swap_b32_e32 v139, v141
	v_and_b32_e32 v194, 0xffff0000, v134
	v_lshlrev_b32_e32 v134, 16, v134
	v_and_b32_e32 v195, 0xffff0000, v135
	v_lshlrev_b32_e32 v135, 16, v135
	v_fma_f32 v74, v74, 0.5, v134
	v_fma_f32 v75, v75, 0.5, v194
	v_fma_f32 v76, v76, 0.5, v135
	v_fma_f32 v77, v77, 0.5, v195
	v_and_b32_e32 v194, 0xffff0000, v136
	v_lshlrev_b32_e32 v136, 16, v136
	v_and_b32_e32 v195, 0xffff0000, v137
	v_lshlrev_b32_e32 v137, 16, v137
	v_fma_f32 v62, v62, 0.5, v136
	v_fma_f32 v63, v63, 0.5, v194
	v_fma_f32 v64, v64, 0.5, v137
	v_fma_f32 v65, v65, 0.5, v195
	v_and_b32_e32 v194, 0xffff0000, v138
	v_lshlrev_b32_e32 v138, 16, v138
	v_and_b32_e32 v195, 0xffff0000, v139
	v_lshlrev_b32_e32 v139, 16, v139
	v_fma_f32 v50, v50, 0.5, v138
	v_fma_f32 v51, v51, 0.5, v194
	v_fma_f32 v52, v52, 0.5, v139
	v_fma_f32 v53, v53, 0.5, v195
	v_and_b32_e32 v194, 0xffff0000, v140
	v_lshlrev_b32_e32 v140, 16, v140
	v_and_b32_e32 v195, 0xffff0000, v141
	v_lshlrev_b32_e32 v141, 16, v141
	v_fma_f32 v34, v34, 0.5, v140
	v_fma_f32 v35, v35, 0.5, v194
	v_fma_f32 v36, v36, 0.5, v141
	v_fma_f32 v37, v37, 0.5, v195
	v_add_u32_e32 v193, 0xb0000, v191
	global_store_dwordx4 v193, v[74:77], s[12:13]
	global_store_dwordx4 v193, v[62:65], s[12:13] offset:64
	global_store_dwordx4 v193, v[50:53], s[12:13] offset:512
	global_store_dwordx4 v193, v[34:37], s[12:13] offset:576
	s_branch .Lp9e_done
